# on top of the combined version: exact vmcnt counts at the two LDS-store points of the three GEMM k-loops (8 newer tile loads stay in flight), prologue loads reordered to match
# baseline (speedup 1.0000x reference)
.LBB0_119:
	s_mul_hi_u32 s5, s4, s21
	s_mul_i32 s10, s5, s18
	s_sub_i32 s10, s4, s10
	s_add_i32 s11, s5, 1
	s_sub_i32 s12, s10, s18
	s_cmp_ge_u32 s10, s18
	s_cselect_b32 s5, s11, s5
	s_cselect_b32 s10, s12, s10
	s_add_i32 s11, s5, 1
	s_cmp_ge_u32 s10, s18
	s_cselect_b32 s5, s11, s5
	s_mul_i32 s10, s5, s18
	s_sub_i32 s4, s4, s10
	s_mul_hi_i32 s10, s4, 0x38e38e39
	s_lshr_b32 s11, s10, 31
	s_ashr_i32 s10, s10, 1
	s_add_i32 s10, s10, s11
	s_mul_i32 s11, s10, 9
	s_mul_i32 s5, s5, 9
	s_sub_i32 s4, s4, s11
	s_add_i32 s11, s4, s5
	s_lshl_b32 s4, s10, 10
	s_or_b32 s29, s4, s19
	s_lshl_b32 s12, s11, 7
	s_mul_i32 s4, s29, 0x880
	s_mul_hi_i32 s5, s29, 0x880
	s_add_u32 s4, s82, s4
	s_addc_u32 s5, s83, s5
	v_readlane_b32 s80, v242, 1
	v_mov_b32_e32 v64, v218
	s_mul_i32 s11, s11, 0x44000
	v_readlane_b32 s82, v242, 3
	s_mul_hi_i32 s13, s12, 0x880
	v_add_u32_e32 v6, 0x100, v64
	v_readlane_b32 s83, v242, 4
	s_add_u32 s10, s82, s11
	v_lshlrev_b32_e32 v0, 4, v64
	v_ashrrev_i32_e32 v67, 3, v6
	v_add_u32_e32 v6, 0x200, v64
	s_addc_u32 s11, s83, s13
	v_and_b32_e32 v128, 0x70, v0
	v_ashrrev_i32_e32 v68, 3, v6
	v_add_u32_e32 v6, 0x300, v64
	v_lshl_add_u64 v[0:1], s[4:5], 0, v[128:129]
	v_lshl_add_u64 v[2:3], s[10:11], 0, v[128:129]
	v_ashrrev_i32_e32 v66, 3, v64
	v_ashrrev_i32_e32 v69, 3, v6
	v_mad_i64_i32 v[4:5], s[14:15], v66, s22, v[0:1]
	v_mad_i64_i32 v[12:13], s[14:15], v66, s22, v[2:3]
	v_mad_i64_i32 v[20:21], s[14:15], v67, s22, v[0:1]
	v_mad_i64_i32 v[28:29], s[14:15], v67, s22, v[2:3]
	v_mad_i64_i32 v[36:37], s[14:15], v68, s22, v[0:1]
	v_mad_i64_i32 v[44:45], s[14:15], v68, s22, v[2:3]
	v_mad_i64_i32 v[52:53], s[14:15], v69, s22, v[0:1]
	v_mad_i64_i32 v[60:61], s[14:15], v69, s22, v[2:3]
	global_load_dwordx4 v[0:3], v[4:5], off
	s_nop 0
	global_load_dwordx4 v[8:11], v[12:13], off
	s_nop 0
	global_load_dwordx4 v[16:19], v[20:21], off
	s_nop 0
	global_load_dwordx4 v[24:27], v[28:29], off
	s_nop 0
	global_load_dwordx4 v[32:35], v[36:37], off
	s_nop 0
	global_load_dwordx4 v[40:43], v[44:45], off
	s_nop 0
	global_load_dwordx4 v[48:51], v[52:53], off
	s_nop 0
	global_load_dwordx4 v[56:59], v[60:61], off
	s_nop 0
	global_load_dwordx4 v[4:7], v[4:5], off offset:128
	s_nop 0
	global_load_dwordx4 v[12:15], v[12:13], off offset:128
	s_nop 0
	global_load_dwordx4 v[20:23], v[20:21], off offset:128
	s_nop 0
	global_load_dwordx4 v[28:31], v[28:29], off offset:128
	s_nop 0
	global_load_dwordx4 v[36:39], v[36:37], off offset:128
	s_nop 0
	global_load_dwordx4 v[44:47], v[44:45], off offset:128
	s_nop 0
	global_load_dwordx4 v[52:55], v[52:53], off offset:128
	s_nop 0
	global_load_dwordx4 v[60:63], v[60:61], off offset:128
	v_and_b32_e32 v65, 15, v64
	v_lshrrev_b32_e32 v71, 1, v64
	s_mov_b32 s13, 0x7ffffc0
	v_and_b32_e32 v70, 48, v64
	v_and_or_b32 v65, v71, s13, v65
	v_and_b32_e32 v71, 0x4f, v64
	v_and_b32_e32 v64, 7, v64
	v_readlane_b32 s81, v242, 2
	v_readlane_b32 s84, v242, 5
	v_readlane_b32 s85, v242, 6
	v_readlane_b32 s86, v242, 7
	v_readlane_b32 s87, v242, 8
	v_mad_u64_u32 v[130:131], s[14:15], v66, s23, v[128:129]
	v_mad_u64_u32 v[132:133], s[14:15], v67, s23, v[128:129]
	v_mad_u64_u32 v[134:135], s[14:15], v68, s23, v[128:129]
	v_mad_u64_u32 v[136:137], s[14:15], v69, s23, v[128:129]
	v_mul_lo_u32 v72, v65, s23
	v_lshlrev_b32_e32 v128, 4, v64
	v_mov_b64_e32 v[64:65], s[10:11]
	v_mul_u32_u24_e32 v71, 0xa0, v71
	v_mad_i64_i32 v[138:139], s[10:11], v66, s22, v[64:65]
	v_mad_i64_i32 v[140:141], s[10:11], v67, s22, v[64:65]
	v_mad_i64_i32 v[142:143], s[10:11], v68, s22, v[64:65]
	v_mad_i64_i32 v[144:145], s[10:11], v69, s22, v[64:65]
	v_mov_b64_e32 v[64:65], s[4:5]
	v_readlane_b32 s80, v242, 25
	v_mad_i64_i32 v[146:147], s[4:5], v66, s22, v[64:65]
	v_mad_i64_i32 v[148:149], s[4:5], v67, s22, v[64:65]
	v_mad_i64_i32 v[150:151], s[4:5], v68, s22, v[64:65]
	v_mad_i64_i32 v[152:153], s[4:5], v69, s22, v[64:65]
	v_add_u32_e32 v131, v70, v72
	v_add_u32_e32 v133, v70, v71
	s_mov_b32 s10, 0
	v_mov_b32_e32 v64, v129
	v_mov_b32_e32 v65, v129
	v_mov_b32_e32 v66, v129
	v_mov_b32_e32 v67, v129
	v_mov_b32_e32 v68, v129
	v_mov_b32_e32 v69, v129
	v_mov_b32_e32 v70, v129
	v_mov_b32_e32 v71, v129
	v_mov_b32_e32 v72, v129
	v_mov_b32_e32 v73, v129
	v_mov_b32_e32 v74, v129
	v_mov_b32_e32 v75, v129
	v_mov_b32_e32 v76, v129
	v_mov_b32_e32 v77, v129
	v_mov_b32_e32 v78, v129
	v_mov_b32_e32 v79, v129
	v_mov_b32_e32 v80, v129
	v_mov_b32_e32 v81, v129
	v_mov_b32_e32 v82, v129
	v_mov_b32_e32 v83, v129
	v_mov_b32_e32 v84, v129
	v_mov_b32_e32 v85, v129
	v_mov_b32_e32 v86, v129
	v_mov_b32_e32 v87, v129
	v_mov_b32_e32 v88, v129
	v_mov_b32_e32 v89, v129
	v_mov_b32_e32 v90, v129
	v_mov_b32_e32 v91, v129
	v_mov_b32_e32 v92, v129
	v_mov_b32_e32 v93, v129
	v_mov_b32_e32 v94, v129
	v_mov_b32_e32 v95, v129
	v_mov_b32_e32 v96, v129
	v_mov_b32_e32 v97, v129
	v_mov_b32_e32 v98, v129
	v_mov_b32_e32 v99, v129
	v_mov_b32_e32 v100, v129
	v_mov_b32_e32 v101, v129
	v_mov_b32_e32 v102, v129
	v_mov_b32_e32 v103, v129
	v_mov_b32_e32 v104, v129
	v_mov_b32_e32 v105, v129
	v_mov_b32_e32 v106, v129
	v_mov_b32_e32 v107, v129
	v_mov_b32_e32 v108, v129
	v_mov_b32_e32 v109, v129
	v_mov_b32_e32 v110, v129
	v_mov_b32_e32 v111, v129
	v_mov_b32_e32 v112, v129
	v_mov_b32_e32 v113, v129
	v_mov_b32_e32 v114, v129
	v_mov_b32_e32 v115, v129
	v_mov_b32_e32 v116, v129
	v_mov_b32_e32 v117, v129
	v_mov_b32_e32 v118, v129
	v_mov_b32_e32 v119, v129
	v_mov_b32_e32 v120, v129
	v_mov_b32_e32 v121, v129
	v_mov_b32_e32 v122, v129
	v_mov_b32_e32 v123, v129
	v_mov_b32_e32 v124, v129
	v_mov_b32_e32 v125, v129
	v_mov_b32_e32 v126, v129
	v_mov_b32_e32 v127, v129
	v_readlane_b32 s82, v242, 27
	v_readlane_b32 s83, v242, 28
	v_readlane_b32 s88, v242, 9
	v_readlane_b32 s89, v242, 10
	v_readlane_b32 s90, v242, 11
	v_readlane_b32 s91, v242, 12
	v_readlane_b32 s92, v242, 13
	v_readlane_b32 s93, v242, 14
	v_readlane_b32 s94, v242, 15
	v_readlane_b32 s95, v242, 16
	v_readlane_b32 s81, v242, 26
	v_readlane_b32 s84, v242, 29
	v_readlane_b32 s85, v242, 30
	v_readlane_b32 s86, v242, 31
	v_readlane_b32 s87, v242, 32
	s_branch .LBB0_121

.LBB0_121:
	s_cmpk_gt_u32 s10, 0x37f
	s_cselect_b64 s[4:5], -1, 0
	s_and_b64 vcc, exec, s[4:5]
	v_lshl_add_u64 v[168:169], v[146:147], 0, v[128:129]
	v_lshl_add_u64 v[166:167], v[138:139], 0, v[128:129]
	v_lshl_add_u64 v[164:165], v[148:149], 0, v[128:129]
	v_lshl_add_u64 v[162:163], v[140:141], 0, v[128:129]
	v_lshl_add_u64 v[160:161], v[150:151], 0, v[128:129]
	v_lshl_add_u64 v[158:159], v[142:143], 0, v[128:129]
	v_lshl_add_u64 v[156:157], v[152:153], 0, v[128:129]
	v_lshl_add_u64 v[154:155], v[144:145], 0, v[128:129]
	s_barrier
	s_waitcnt vmcnt(15)
	ds_write_b128 v130, v[0:3]
	s_waitcnt vmcnt(14)
	ds_write_b128 v130, v[8:11] offset:20480
	s_waitcnt vmcnt(13)
	ds_write_b128 v132, v[16:19]
	s_waitcnt vmcnt(12)
	ds_write_b128 v132, v[24:27] offset:20480
	s_waitcnt vmcnt(11)
	ds_write_b128 v134, v[32:35]
	s_waitcnt vmcnt(10)
	ds_write_b128 v134, v[40:43] offset:20480
	s_waitcnt vmcnt(9)
	ds_write_b128 v136, v[48:51]
	s_waitcnt vmcnt(8)
	ds_write_b128 v136, v[56:59] offset:20480
	s_waitcnt lgkmcnt(0)
	s_barrier
	s_cbranch_vccnz .LBB0_123
	global_load_dwordx4 v[0:3], v[168:169], off offset:256
	global_load_dwordx4 v[8:11], v[166:167], off offset:256
	global_load_dwordx4 v[16:19], v[164:165], off offset:256
	global_load_dwordx4 v[24:27], v[162:163], off offset:256
	global_load_dwordx4 v[32:35], v[160:161], off offset:256
	global_load_dwordx4 v[40:43], v[158:159], off offset:256
	global_load_dwordx4 v[48:51], v[156:157], off offset:256
	global_load_dwordx4 v[56:59], v[154:155], off offset:256
.LBB0_123:
	ds_read_b128 v[174:177], v131
	ds_read_b128 v[178:181], v131 offset:2560
	ds_read_b128 v[182:185], v131 offset:5120
	ds_read_b128 v[186:189], v131 offset:7680
	ds_read_b128 v[190:193], v133 offset:20480
	ds_read_b128 v[194:197], v133 offset:23040
	ds_read_b128 v[198:201], v133 offset:25600
	ds_read_b128 v[202:205], v133 offset:28160
	s_setprio 1
	s_waitcnt lgkmcnt(3)
	v_mfma_f32_16x16x32_bf16 v[124:127], v[174:177], v[190:193], v[124:127]
	s_waitcnt lgkmcnt(2)
	v_mfma_f32_16x16x32_bf16 v[120:123], v[174:177], v[194:197], v[120:123]
	s_waitcnt lgkmcnt(1)
	v_mfma_f32_16x16x32_bf16 v[116:119], v[174:177], v[198:201], v[116:119]
	s_waitcnt lgkmcnt(0)
	v_mfma_f32_16x16x32_bf16 v[112:115], v[174:177], v[202:205], v[112:115]
	v_mfma_f32_16x16x32_bf16 v[108:111], v[178:181], v[190:193], v[108:111]
	v_mfma_f32_16x16x32_bf16 v[104:107], v[178:181], v[194:197], v[104:107]
	v_mfma_f32_16x16x32_bf16 v[100:103], v[178:181], v[198:201], v[100:103]
	v_mfma_f32_16x16x32_bf16 v[96:99], v[178:181], v[202:205], v[96:99]
	v_mfma_f32_16x16x32_bf16 v[174:177], v[182:185], v[190:193], v[92:95]
	v_mfma_f32_16x16x32_bf16 v[178:181], v[182:185], v[194:197], v[88:91]
	v_mfma_f32_16x16x32_bf16 v[206:209], v[182:185], v[198:201], v[84:87]
	v_mfma_f32_16x16x32_bf16 v[182:185], v[182:185], v[202:205], v[80:83]
	v_mfma_f32_16x16x32_bf16 v[190:193], v[186:189], v[190:193], v[76:79]
	v_mfma_f32_16x16x32_bf16 v[194:197], v[186:189], v[194:197], v[72:75]
	v_mfma_f32_16x16x32_bf16 v[198:201], v[186:189], v[198:201], v[68:71]
	v_mfma_f32_16x16x32_bf16 v[186:189], v[186:189], v[202:205], v[64:67]
	s_setprio 0
	ds_read_b128 v[76:79], v131 offset:64
	ds_read_b128 v[92:95], v131 offset:2624
	ds_read_b128 v[202:205], v131 offset:5184
	ds_read_b128 v[210:213], v131 offset:7744
	ds_read_b128 v[214:217], v133 offset:20544
	ds_read_b128 v[220:223], v133 offset:23104
	ds_read_b128 v[224:227], v133 offset:25664
	ds_read_b128 v[228:231], v133 offset:28224
	s_setprio 1
	s_waitcnt lgkmcnt(3)
	v_mfma_f32_16x16x32_bf16 v[64:67], v[76:79], v[214:217], v[124:127]
	s_waitcnt lgkmcnt(2)
	v_mfma_f32_16x16x32_bf16 v[68:71], v[76:79], v[220:223], v[120:123]
	s_waitcnt lgkmcnt(1)
	v_mfma_f32_16x16x32_bf16 v[72:75], v[76:79], v[224:227], v[116:119]
	s_waitcnt lgkmcnt(0)
	v_mfma_f32_16x16x32_bf16 v[76:79], v[76:79], v[228:231], v[112:115]
	v_mfma_f32_16x16x32_bf16 v[80:83], v[92:95], v[214:217], v[108:111]
	v_mfma_f32_16x16x32_bf16 v[84:87], v[92:95], v[220:223], v[104:107]
	v_mfma_f32_16x16x32_bf16 v[88:91], v[92:95], v[224:227], v[100:103]
	v_mfma_f32_16x16x32_bf16 v[92:95], v[92:95], v[228:231], v[96:99]
	v_mfma_f32_16x16x32_bf16 v[96:99], v[202:205], v[214:217], v[174:177]
	v_mfma_f32_16x16x32_bf16 v[100:103], v[202:205], v[220:223], v[178:181]
	v_mfma_f32_16x16x32_bf16 v[104:107], v[202:205], v[224:227], v[206:209]
	v_mfma_f32_16x16x32_bf16 v[108:111], v[202:205], v[228:231], v[182:185]
	v_mfma_f32_16x16x32_bf16 v[112:115], v[210:213], v[214:217], v[190:193]
	v_mfma_f32_16x16x32_bf16 v[116:119], v[210:213], v[220:223], v[194:197]
	v_mfma_f32_16x16x32_bf16 v[120:123], v[210:213], v[224:227], v[198:201]
	v_mfma_f32_16x16x32_bf16 v[124:127], v[210:213], v[228:231], v[186:189]
	s_setprio 0
	s_cmpk_gt_u32 s10, 0x37f
	s_cbranch_scc0 .Lgvm_0
	s_waitcnt vmcnt(0)
.Lgvm_0:
	s_cmpk_gt_u32 s10, 0x33f
	s_barrier
	s_waitcnt vmcnt(15)
	ds_write_b128 v130, v[4:7]
	s_waitcnt vmcnt(14)
	ds_write_b128 v130, v[12:15] offset:20480
	s_waitcnt vmcnt(13)
	ds_write_b128 v132, v[20:23]
	s_waitcnt vmcnt(12)
	ds_write_b128 v132, v[28:31] offset:20480
	s_waitcnt vmcnt(11)
	ds_write_b128 v134, v[36:39]
	s_waitcnt vmcnt(10)
	ds_write_b128 v134, v[44:47] offset:20480
	s_waitcnt vmcnt(9)
	ds_write_b128 v136, v[52:55]
	s_waitcnt vmcnt(8)
	ds_write_b128 v136, v[60:63] offset:20480
	s_waitcnt lgkmcnt(0)
	s_barrier
	s_cbranch_scc1 .LBB0_120
	global_load_dwordx4 v[4:7], v[168:169], off offset:384
	global_load_dwordx4 v[12:15], v[166:167], off offset:384
	global_load_dwordx4 v[20:23], v[164:165], off offset:384
	global_load_dwordx4 v[28:31], v[162:163], off offset:384
	global_load_dwordx4 v[36:39], v[160:161], off offset:384
	global_load_dwordx4 v[44:47], v[158:159], off offset:384
	global_load_dwordx4 v[52:55], v[156:157], off offset:384
	global_load_dwordx4 v[60:63], v[154:155], off offset:384
	s_branch .LBB0_120

.LBB0_955:
	s_and_b32 s0, s9, 0x1fffff8
	s_or_b32 s0, s0, s3
	s_lshl_b32 s4, s0, 7
	v_mov_b32_e32 v80, v218
	s_and_b32 s8, s9, 7
	s_lshl_b64 s[0:1], s[4:5], 11
	s_add_u32 s18, s86, s0
	v_add_u32_e32 v6, 0x100, v80
	v_readlane_b32 s36, v242, 1
	v_ashrrev_i32_e32 v68, 3, v6
	v_add_u32_e32 v6, 0x200, v80
	s_addc_u32 s19, s87, s1
	s_lshl_b32 s0, s8, 18
	v_readlane_b32 s40, v242, 5
	v_ashrrev_i32_e32 v72, 3, v6
	v_add_u32_e32 v6, 0x300, v80
	v_readlane_b32 s41, v242, 6
	s_add_u32 s0, s40, s0
	v_lshlrev_b32_e32 v0, 4, v80
	v_ashrrev_i32_e32 v64, 3, v80
	v_ashrrev_i32_e32 v76, 3, v6
	s_addc_u32 s1, s41, 0
	v_and_b32_e32 v128, 0x70, v0
	v_ashrrev_i32_e32 v65, 31, v64
	v_ashrrev_i32_e32 v69, 31, v68
	v_ashrrev_i32_e32 v73, 31, v72
	v_ashrrev_i32_e32 v77, 31, v76
	v_lshl_add_u64 v[0:1], s[18:19], 0, v[128:129]
	v_lshl_add_u64 v[2:3], s[0:1], 0, v[128:129]
	v_lshlrev_b64 v[66:67], 11, v[64:65]
	v_lshlrev_b64 v[70:71], 11, v[68:69]
	v_lshlrev_b64 v[74:75], 11, v[72:73]
	v_lshlrev_b64 v[78:79], 11, v[76:77]
	v_lshl_add_u64 v[4:5], v[0:1], 0, v[66:67]
	v_lshl_add_u64 v[12:13], v[2:3], 0, v[66:67]
	v_lshl_add_u64 v[20:21], v[0:1], 0, v[70:71]
	v_lshl_add_u64 v[28:29], v[2:3], 0, v[70:71]
	v_lshl_add_u64 v[36:37], v[0:1], 0, v[74:75]
	v_lshl_add_u64 v[44:45], v[2:3], 0, v[74:75]
	v_lshl_add_u64 v[52:53], v[0:1], 0, v[78:79]
	v_lshl_add_u64 v[60:61], v[2:3], 0, v[78:79]
	global_load_dwordx4 v[0:3], v[4:5], off
	s_nop 0
	global_load_dwordx4 v[8:11], v[12:13], off
	s_nop 0
	global_load_dwordx4 v[16:19], v[20:21], off
	s_waitcnt lgkmcnt(0)
	global_load_dwordx4 v[24:27], v[28:29], off
	s_nop 0
	global_load_dwordx4 v[32:35], v[36:37], off
	s_nop 0
	global_load_dwordx4 v[40:43], v[44:45], off
	s_nop 0
	global_load_dwordx4 v[48:51], v[52:53], off
	s_nop 0
	global_load_dwordx4 v[56:59], v[60:61], off
	s_nop 0
	global_load_dwordx4 v[4:7], v[4:5], off offset:128
	s_nop 0
	global_load_dwordx4 v[12:15], v[12:13], off offset:128
	s_nop 0
	global_load_dwordx4 v[20:23], v[20:21], off offset:128
	s_nop 0
	global_load_dwordx4 v[28:31], v[28:29], off offset:128
	s_nop 0
	global_load_dwordx4 v[36:39], v[36:37], off offset:128
	s_nop 0
	global_load_dwordx4 v[44:47], v[44:45], off offset:128
	s_nop 0
	global_load_dwordx4 v[52:55], v[52:53], off offset:128
	s_nop 0
	global_load_dwordx4 v[60:63], v[60:61], off offset:128
	v_lshl_add_u64 v[138:139], s[0:1], 0, v[66:67]
	v_lshl_add_u64 v[140:141], s[0:1], 0, v[70:71]
	v_lshl_add_u64 v[142:143], s[0:1], 0, v[74:75]
	v_lshl_add_u64 v[144:145], s[0:1], 0, v[78:79]
	s_lshl_b32 s0, s9, 7
	s_and_b32 s0, s0, 0xfffffc00
	s_or_b32 s0, s13, s0
	s_mov_b32 s1, s5
	v_and_b32_e32 v65, 15, v80
	v_lshrrev_b32_e32 v73, 1, v80
	s_lshl_b64 s[0:1], s[0:1], 11
	v_and_or_b32 v65, v73, s14, v65
	v_and_b32_e32 v73, 0x4f, v80
	s_add_u32 s0, s86, s0
	v_and_b32_e32 v69, 48, v80
	v_mad_u64_u32 v[130:131], s[18:19], v64, s15, v[128:129]
	v_mad_u64_u32 v[132:133], s[18:19], v68, s15, v[128:129]
	v_mul_lo_u32 v64, v65, s15
	v_mul_u32_u24_e32 v65, 0xa0, v73
	v_and_b32_e32 v68, 7, v80
	s_addc_u32 s1, s87, s1
	v_mad_u64_u32 v[134:135], s[18:19], v72, s15, v[128:129]
	v_mad_u64_u32 v[136:137], s[18:19], v76, s15, v[128:129]
	v_lshlrev_b32_e32 v128, 4, v68
	v_lshl_add_u64 v[146:147], s[0:1], 0, v[66:67]
	v_lshl_add_u64 v[148:149], s[0:1], 0, v[70:71]
	v_lshl_add_u64 v[150:151], s[0:1], 0, v[74:75]
	v_lshl_add_u64 v[152:153], s[0:1], 0, v[78:79]
	v_add_u32_e32 v131, v69, v64
	v_add_u32_e32 v133, v69, v65
	s_mov_b32 s9, 0
	v_mov_b32_e32 v64, v129
	v_mov_b32_e32 v65, v129
	v_mov_b32_e32 v66, v129
	v_mov_b32_e32 v67, v129
	v_mov_b32_e32 v68, v129
	v_mov_b32_e32 v69, v129
	v_mov_b32_e32 v70, v129
	v_mov_b32_e32 v71, v129
	v_mov_b32_e32 v72, v129
	v_mov_b32_e32 v73, v129
	v_mov_b32_e32 v74, v129
	v_mov_b32_e32 v75, v129
	v_mov_b32_e32 v76, v129
	v_mov_b32_e32 v77, v129
	v_mov_b32_e32 v78, v129
	v_mov_b32_e32 v79, v129
	v_mov_b32_e32 v80, v129
	v_mov_b32_e32 v81, v129
	v_mov_b32_e32 v82, v129
	v_mov_b32_e32 v83, v129
	v_mov_b32_e32 v84, v129
	v_mov_b32_e32 v85, v129
	v_mov_b32_e32 v86, v129
	v_mov_b32_e32 v87, v129
	v_mov_b32_e32 v88, v129
	v_mov_b32_e32 v89, v129
	v_mov_b32_e32 v90, v129
	v_mov_b32_e32 v91, v129
	s_waitcnt vmcnt(20)
	v_mov_b32_e32 v92, v129
	v_mov_b32_e32 v93, v129
	v_mov_b32_e32 v94, v129
	v_mov_b32_e32 v95, v129
	v_mov_b32_e32 v96, v129
	v_mov_b32_e32 v97, v129
	v_mov_b32_e32 v98, v129
	v_mov_b32_e32 v99, v129
	v_mov_b32_e32 v100, v129
	v_mov_b32_e32 v101, v129
	v_mov_b32_e32 v102, v129
	v_mov_b32_e32 v103, v129
	v_mov_b32_e32 v104, v129
	v_mov_b32_e32 v105, v129
	v_mov_b32_e32 v106, v129
	v_mov_b32_e32 v107, v129
	v_mov_b32_e32 v108, v129
	v_mov_b32_e32 v109, v129
	v_mov_b32_e32 v110, v129
	v_mov_b32_e32 v111, v129
	v_mov_b32_e32 v112, v129
	v_mov_b32_e32 v113, v129
	v_mov_b32_e32 v114, v129
	v_mov_b32_e32 v115, v129
	v_mov_b32_e32 v116, v129
	v_mov_b32_e32 v117, v129
	v_mov_b32_e32 v118, v129
	v_mov_b32_e32 v119, v129
	v_mov_b32_e32 v120, v129
	v_mov_b32_e32 v121, v129
	v_mov_b32_e32 v122, v129
	v_mov_b32_e32 v123, v129
	v_mov_b32_e32 v124, v129
	v_mov_b32_e32 v125, v129
	v_mov_b32_e32 v126, v129
	v_mov_b32_e32 v127, v129
	v_readlane_b32 s37, v242, 2
	v_readlane_b32 s38, v242, 3
	v_readlane_b32 s39, v242, 4
	v_readlane_b32 s42, v242, 7
	v_readlane_b32 s43, v242, 8
	v_readlane_b32 s44, v242, 9
	v_readlane_b32 s45, v242, 10
	v_readlane_b32 s46, v242, 11
	v_readlane_b32 s47, v242, 12
	v_readlane_b32 s48, v242, 13
	v_readlane_b32 s49, v242, 14
	v_readlane_b32 s50, v242, 15
	v_readlane_b32 s51, v242, 16
	s_branch .LBB0_957

.LBB0_957:
	s_cmpk_gt_u32 s9, 0x37f
	s_cselect_b64 s[0:1], -1, 0
	s_and_b64 vcc, exec, s[0:1]
	v_lshl_add_u64 v[168:169], v[146:147], 0, v[128:129]
	v_lshl_add_u64 v[166:167], v[138:139], 0, v[128:129]
	v_lshl_add_u64 v[164:165], v[148:149], 0, v[128:129]
	v_lshl_add_u64 v[162:163], v[140:141], 0, v[128:129]
	v_lshl_add_u64 v[160:161], v[150:151], 0, v[128:129]
	v_lshl_add_u64 v[158:159], v[142:143], 0, v[128:129]
	v_lshl_add_u64 v[156:157], v[152:153], 0, v[128:129]
	v_lshl_add_u64 v[154:155], v[144:145], 0, v[128:129]
	s_barrier
	s_waitcnt vmcnt(15)
	ds_write_b128 v130, v[0:3]
	s_waitcnt vmcnt(14)
	ds_write_b128 v130, v[8:11] offset:20480
	s_waitcnt vmcnt(13)
	ds_write_b128 v132, v[16:19]
	s_waitcnt vmcnt(12)
	ds_write_b128 v132, v[24:27] offset:20480
	s_waitcnt vmcnt(11)
	ds_write_b128 v134, v[32:35]
	s_waitcnt vmcnt(10)
	ds_write_b128 v134, v[40:43] offset:20480
	s_waitcnt vmcnt(9)
	ds_write_b128 v136, v[48:51]
	s_waitcnt vmcnt(8)
	ds_write_b128 v136, v[56:59] offset:20480
	s_waitcnt lgkmcnt(0)
	s_barrier
	s_cbranch_vccnz .LBB0_959
	global_load_dwordx4 v[0:3], v[168:169], off offset:256
	global_load_dwordx4 v[8:11], v[166:167], off offset:256
	global_load_dwordx4 v[16:19], v[164:165], off offset:256
	global_load_dwordx4 v[24:27], v[162:163], off offset:256
	global_load_dwordx4 v[32:35], v[160:161], off offset:256
	global_load_dwordx4 v[40:43], v[158:159], off offset:256
	global_load_dwordx4 v[48:51], v[156:157], off offset:256
	global_load_dwordx4 v[56:59], v[154:155], off offset:256

.Lfv_3:
	s_cmpk_gt_u32 s9, 0x37f
	s_cbranch_scc0 .Lgvm_1
	s_waitcnt vmcnt(0)
.Lgvm_1:
	s_cmpk_gt_u32 s9, 0x33f
	s_barrier
	s_waitcnt vmcnt(15)
	ds_write_b128 v130, v[4:7]
	s_waitcnt vmcnt(14)
	ds_write_b128 v130, v[12:15] offset:20480
	s_waitcnt vmcnt(13)
	ds_write_b128 v132, v[20:23]
	s_waitcnt vmcnt(12)
	ds_write_b128 v132, v[28:31] offset:20480
	s_waitcnt vmcnt(11)
	ds_write_b128 v134, v[36:39]
	s_waitcnt vmcnt(10)
	ds_write_b128 v134, v[44:47] offset:20480
	s_waitcnt vmcnt(9)
	ds_write_b128 v136, v[52:55]
	s_waitcnt vmcnt(8)
	ds_write_b128 v136, v[60:63] offset:20480
	s_waitcnt lgkmcnt(0)
	s_barrier
	s_cbranch_scc1 .LBB0_956
	global_load_dwordx4 v[4:7], v[168:169], off offset:384
	global_load_dwordx4 v[12:15], v[166:167], off offset:384
	global_load_dwordx4 v[20:23], v[164:165], off offset:384
	global_load_dwordx4 v[28:31], v[162:163], off offset:384
	global_load_dwordx4 v[36:39], v[160:161], off offset:384
	global_load_dwordx4 v[44:47], v[158:159], off offset:384
	global_load_dwordx4 v[52:55], v[156:157], off offset:384
	global_load_dwordx4 v[60:63], v[154:155], off offset:384
	s_branch .LBB0_956

.LBB0_1596:
	s_and_b32 s0, s4, 0x1fffff8
	s_or_b32 s0, s0, s3
	s_lshl_b32 s10, s0, 7
	s_and_b32 s6, s4, 7
	s_lshl_b64 s[0:1], s[10:11], 11
	s_waitcnt vmcnt(4)
	v_mov_b32_e32 v92, v218
	s_add_u32 s8, s82, s0
	v_readlane_b32 s36, v242, 1
	s_addc_u32 s9, s83, s1
	v_add_u32_e32 v4, 0x100, v92
	s_lshl_b32 s0, s6, 18
	v_readlane_b32 s44, v242, 9
	v_ashrrev_i32_e32 v68, 3, v4
	v_add_u32_e32 v4, 0x200, v92
	v_readlane_b32 s45, v242, 10
	s_add_u32 s0, s44, s0
	v_lshlrev_b32_e32 v0, 4, v92
	s_waitcnt vmcnt(2)
	v_ashrrev_i32_e32 v64, 3, v92
	s_waitcnt vmcnt(1)
	v_ashrrev_i32_e32 v76, 3, v4
	v_add_u32_e32 v4, 0x300, v92
	s_addc_u32 s1, s45, 0
	v_and_b32_e32 v128, 0x70, v0
	v_ashrrev_i32_e32 v65, 31, v64
	s_waitcnt vmcnt(0)
	v_ashrrev_i32_e32 v84, 3, v4
	v_lshl_add_u64 v[0:1], s[8:9], 0, v[128:129]
	v_lshl_add_u64 v[2:3], s[0:1], 0, v[128:129]
	v_lshlrev_b64 v[66:67], 11, v[64:65]
	v_ashrrev_i32_e32 v69, 31, v68
	v_ashrrev_i32_e32 v77, 31, v76
	v_ashrrev_i32_e32 v85, 31, v84
	v_lshl_add_u64 v[60:61], v[0:1], 0, v[66:67]
	v_lshl_add_u64 v[62:63], v[2:3], 0, v[66:67]
	v_lshlrev_b64 v[70:71], 11, v[68:69]
	v_lshlrev_b64 v[78:79], 11, v[76:77]
	v_lshlrev_b64 v[86:87], 11, v[84:85]
	v_lshl_add_u64 v[72:73], v[0:1], 0, v[70:71]
	v_lshl_add_u64 v[74:75], v[2:3], 0, v[70:71]
	v_lshl_add_u64 v[80:81], v[0:1], 0, v[78:79]
	v_lshl_add_u64 v[82:83], v[2:3], 0, v[78:79]
	v_lshl_add_u64 v[88:89], v[0:1], 0, v[86:87]
	v_lshl_add_u64 v[90:91], v[2:3], 0, v[86:87]
	global_load_dwordx4 v[0:3], v[60:61], off
	global_load_dwordx4 v[8:11], v[62:63], off
	global_load_dwordx4 v[16:19], v[72:73], off
	s_waitcnt lgkmcnt(0)
	global_load_dwordx4 v[24:27], v[74:75], off
	global_load_dwordx4 v[32:35], v[80:81], off
	global_load_dwordx4 v[40:43], v[82:83], off
	global_load_dwordx4 v[48:51], v[88:89], off
	global_load_dwordx4 v[56:59], v[90:91], off
	global_load_dwordx4 v[4:7], v[60:61], off offset:128
	global_load_dwordx4 v[12:15], v[62:63], off offset:128
	global_load_dwordx4 v[20:23], v[72:73], off offset:128
	global_load_dwordx4 v[28:31], v[74:75], off offset:128
	global_load_dwordx4 v[36:39], v[80:81], off offset:128
	global_load_dwordx4 v[44:47], v[82:83], off offset:128
	global_load_dwordx4 v[52:55], v[88:89], off offset:128
	global_load_dwordx4 v[60:63], v[90:91], off offset:128
	v_lshl_add_u64 v[138:139], s[0:1], 0, v[66:67]
	v_lshl_add_u64 v[140:141], s[0:1], 0, v[70:71]
	v_lshl_add_u64 v[142:143], s[0:1], 0, v[78:79]
	v_lshl_add_u64 v[144:145], s[0:1], 0, v[86:87]
	s_lshl_b32 s0, s4, 7
	s_and_b32 s0, s0, 0xfffffc00
	s_or_b32 s0, s19, s0
	s_mov_b32 s1, s11
	v_and_b32_e32 v65, 15, v92
	v_lshrrev_b32_e32 v72, 1, v92
	s_lshl_b64 s[0:1], s[0:1], 11
	v_and_or_b32 v65, v72, s20, v65
	v_and_b32_e32 v72, 0x4f, v92
	s_add_u32 s0, s82, s0
	v_and_b32_e32 v69, 48, v92
	v_mad_u64_u32 v[130:131], s[8:9], v64, s21, v[128:129]
	v_mad_u64_u32 v[132:133], s[8:9], v68, s21, v[128:129]
	v_mul_lo_u32 v64, v65, s21
	v_mul_u32_u24_e32 v65, 0xa0, v72
	v_and_b32_e32 v68, 7, v92
	s_addc_u32 s1, s83, s1
	v_mad_u64_u32 v[134:135], s[8:9], v76, s21, v[128:129]
	v_mad_u64_u32 v[136:137], s[8:9], v84, s21, v[128:129]
	v_lshlrev_b32_e32 v128, 4, v68
	v_lshl_add_u64 v[146:147], s[0:1], 0, v[66:67]
	v_lshl_add_u64 v[148:149], s[0:1], 0, v[70:71]
	v_lshl_add_u64 v[150:151], s[0:1], 0, v[78:79]
	v_lshl_add_u64 v[152:153], s[0:1], 0, v[86:87]
	v_add_u32_e32 v131, v69, v64
	v_add_u32_e32 v133, v69, v65
	s_mov_b32 s4, 0
	v_mov_b32_e32 v64, v129
	v_mov_b32_e32 v65, v129
	v_mov_b32_e32 v66, v129
	v_mov_b32_e32 v67, v129
	v_mov_b32_e32 v68, v129
	v_mov_b32_e32 v69, v129
	v_mov_b32_e32 v70, v129
	v_mov_b32_e32 v71, v129
	v_mov_b32_e32 v72, v129
	v_mov_b32_e32 v73, v129
	v_mov_b32_e32 v74, v129
	v_mov_b32_e32 v75, v129
	v_mov_b32_e32 v76, v129
	v_mov_b32_e32 v77, v129
	v_mov_b32_e32 v78, v129
	v_mov_b32_e32 v79, v129
	v_mov_b32_e32 v80, v129
	v_mov_b32_e32 v81, v129
	v_mov_b32_e32 v82, v129
	v_mov_b32_e32 v83, v129
	v_mov_b32_e32 v84, v129
	v_mov_b32_e32 v85, v129
	v_mov_b32_e32 v86, v129
	v_mov_b32_e32 v87, v129
	v_mov_b32_e32 v88, v129
	v_mov_b32_e32 v89, v129
	v_mov_b32_e32 v90, v129
	v_mov_b32_e32 v91, v129
	v_mov_b32_e32 v92, v129
	v_mov_b32_e32 v93, v129
	v_mov_b32_e32 v94, v129
	v_mov_b32_e32 v95, v129
	v_mov_b32_e32 v96, v129
	v_mov_b32_e32 v97, v129
	v_mov_b32_e32 v98, v129
	v_mov_b32_e32 v99, v129
	v_mov_b32_e32 v100, v129
	v_mov_b32_e32 v101, v129
	v_mov_b32_e32 v102, v129
	v_mov_b32_e32 v103, v129
	v_mov_b32_e32 v104, v129
	v_mov_b32_e32 v105, v129
	v_mov_b32_e32 v106, v129
	v_mov_b32_e32 v107, v129
	v_mov_b32_e32 v108, v129
	v_mov_b32_e32 v109, v129
	v_mov_b32_e32 v110, v129
	v_mov_b32_e32 v111, v129
	v_mov_b32_e32 v112, v129
	v_mov_b32_e32 v113, v129
	v_mov_b32_e32 v114, v129
	v_mov_b32_e32 v115, v129
	v_mov_b32_e32 v116, v129
	v_mov_b32_e32 v117, v129
	v_mov_b32_e32 v118, v129
	v_mov_b32_e32 v119, v129
	v_mov_b32_e32 v120, v129
	v_mov_b32_e32 v121, v129
	v_mov_b32_e32 v122, v129
	v_mov_b32_e32 v123, v129
	v_mov_b32_e32 v124, v129
	v_mov_b32_e32 v125, v129
	v_mov_b32_e32 v126, v129
	v_mov_b32_e32 v127, v129
	v_readlane_b32 s37, v242, 2
	v_readlane_b32 s38, v242, 3
	v_readlane_b32 s39, v242, 4
	v_readlane_b32 s40, v242, 5
	v_readlane_b32 s41, v242, 6
	v_readlane_b32 s42, v242, 7
	v_readlane_b32 s43, v242, 8
	v_readlane_b32 s46, v242, 11
	v_readlane_b32 s47, v242, 12
	v_readlane_b32 s48, v242, 13
	v_readlane_b32 s49, v242, 14
	v_readlane_b32 s50, v242, 15
	v_readlane_b32 s51, v242, 16
	s_branch .LBB0_1598

.LBB0_1598:
	s_cmpk_gt_u32 s4, 0x37f
	s_cselect_b64 s[0:1], -1, 0
	s_and_b64 vcc, exec, s[0:1]
	v_lshl_add_u64 v[168:169], v[146:147], 0, v[128:129]
	v_lshl_add_u64 v[166:167], v[138:139], 0, v[128:129]
	v_lshl_add_u64 v[164:165], v[148:149], 0, v[128:129]
	v_lshl_add_u64 v[162:163], v[140:141], 0, v[128:129]
	v_lshl_add_u64 v[160:161], v[150:151], 0, v[128:129]
	v_lshl_add_u64 v[158:159], v[142:143], 0, v[128:129]
	v_lshl_add_u64 v[156:157], v[152:153], 0, v[128:129]
	v_lshl_add_u64 v[154:155], v[144:145], 0, v[128:129]
	s_barrier
	s_waitcnt vmcnt(15)
	ds_write_b128 v130, v[0:3]
	s_waitcnt vmcnt(14)
	ds_write_b128 v130, v[8:11] offset:20480
	s_waitcnt vmcnt(13)
	ds_write_b128 v132, v[16:19]
	s_waitcnt vmcnt(12)
	ds_write_b128 v132, v[24:27] offset:20480
	s_waitcnt vmcnt(11)
	ds_write_b128 v134, v[32:35]
	s_waitcnt vmcnt(10)
	ds_write_b128 v134, v[40:43] offset:20480
	s_waitcnt vmcnt(9)
	ds_write_b128 v136, v[48:51]
	s_waitcnt vmcnt(8)
	ds_write_b128 v136, v[56:59] offset:20480
	s_waitcnt lgkmcnt(0)
	s_barrier
	s_cbranch_vccnz .LBB0_1600
	global_load_dwordx4 v[0:3], v[168:169], off offset:256
	global_load_dwordx4 v[8:11], v[166:167], off offset:256
	global_load_dwordx4 v[16:19], v[164:165], off offset:256
	global_load_dwordx4 v[24:27], v[162:163], off offset:256
	global_load_dwordx4 v[32:35], v[160:161], off offset:256
	global_load_dwordx4 v[40:43], v[158:159], off offset:256
	global_load_dwordx4 v[48:51], v[156:157], off offset:256
	global_load_dwordx4 v[56:59], v[154:155], off offset:256

.Lfv_13:
	s_cmpk_gt_u32 s4, 0x37f
	s_cbranch_scc0 .Lgvm_2
	s_waitcnt vmcnt(0)
.Lgvm_2:
	s_cmpk_gt_u32 s4, 0x33f
	s_barrier
	s_waitcnt vmcnt(15)
	ds_write_b128 v130, v[4:7]
	s_waitcnt vmcnt(14)
	ds_write_b128 v130, v[12:15] offset:20480
	s_waitcnt vmcnt(13)
	ds_write_b128 v132, v[20:23]
	s_waitcnt vmcnt(12)
	ds_write_b128 v132, v[28:31] offset:20480
	s_waitcnt vmcnt(11)
	ds_write_b128 v134, v[36:39]
	s_waitcnt vmcnt(10)
	ds_write_b128 v134, v[44:47] offset:20480
	s_waitcnt vmcnt(9)
	ds_write_b128 v136, v[52:55]
	s_waitcnt vmcnt(8)
	ds_write_b128 v136, v[60:63] offset:20480
	s_waitcnt lgkmcnt(0)
	s_barrier
	s_cbranch_scc1 .LBB0_1597
	global_load_dwordx4 v[4:7], v[168:169], off offset:384
	global_load_dwordx4 v[12:15], v[166:167], off offset:384
	global_load_dwordx4 v[20:23], v[164:165], off offset:384
	global_load_dwordx4 v[28:31], v[162:163], off offset:384
	global_load_dwordx4 v[36:39], v[160:161], off offset:384
	global_load_dwordx4 v[44:47], v[158:159], off offset:384
	global_load_dwordx4 v[52:55], v[156:157], off offset:384
	global_load_dwordx4 v[60:63], v[154:155], off offset:384
	s_branch .LBB0_1597
